# P2 start stagger in 8 groups (bi&7) x s_sleep 40 on top of the 8-group P7 stagger
# baseline (speedup 1.0000x reference)
.LBB0_235:
	s_and_b64 vcc, exec, s[0:1]
	s_cbranch_vccz .LBB0_281
	v_readlane_b32 s4, v252, 3
	v_readlane_b32 s6, v252, 5
	s_cmp_gt_i32 s6, 0
	s_mov_b64 s[0:1], -1
	v_readlane_b32 s5, v252, 4
	v_readlane_b32 s7, v252, 6
	s_cbranch_scc0 .LBB0_293
	v_readlane_b32 s4, v252, 3
	v_readlane_b32 s6, v252, 5
	s_cmp_gt_i32 s6, 1
	v_readlane_b32 s5, v252, 4
	v_readlane_b32 s7, v252, 6
	s_cbranch_scc0 .LBB0_283
	v_readlane_b32 s1, v252, 0
	s_mov_b32 s0, s1
	s_ashr_i32 s1, s1, 3
	v_readlane_b32 s4, v254, 6
	s_cmp_ge_i32 s1, s4
	s_cbranch_scc1 .LBB0_282
	s_cmpk_gt_i32 s1, 0x17b
	s_cbranch_scc1 .LBB0_282
	s_and_b32 s0, s0, 7
	s_mulk_i32 s0, 0x17c
	s_add_i32 s6, s0, 0x17c
	s_add_i32 s7, s0, s1
	s_and_b32 s4, s1, 7
.Lp2_stag_loop:
	s_cmp_eq_u32 s4, 0
	s_cbranch_scc1 .Lp2_nostag
	s_sleep 40
	s_add_i32 s4, s4, -1
	s_branch .Lp2_stag_loop
.Lp2_nostag:
	s_branch .LBB0_242
.LBB0_241:
	v_readlane_b32 s0, v254, 6
	s_add_i32 s7, s7, s0
	s_cmp_ge_i32 s7, s6
	s_barrier
	s_cbranch_scc1 .LBB0_282
